# cooperative-groups grid sync after the norm phase replaced by a device-memory counter barrier; cumsum reads batched
# speedup vs baseline: 1.0067x; 1.0067x over previous
; #define LAS __attribute__((address_space(3)))
; __global__ void __launch_bounds__(256, 2) k_mega(Params p) {
;     ...
;   if (threadIdx.x == 0) xb_words = make_uint4(0u, 0u, 0u, 0u);
;   __syncthreads();
;   const XcdBarrier xb = xcd_barrier_post(p.bar, (volatile LAS unsigned*)&xb_words);
;   phase_norm0(p, lds);
;   grid.sync();
; #pragma unroll 1
;   for (int l = 0; l < NL; ++l) {
;     phase_gemm_in(p, l, lds); xcd_barrier(xb);
;     phase_chunk(p, l, lds); xcd_barrier(xb);
;     phase_mix(p, l, lds); xcd_barrier(xb);
;     phase_o(p, l, blockIdx.x, NCH_P / 2, gridDim.x); xcd_barrier(xb);
;     phase_merge(p, l, lds); xcd_barrier(xb);
;     phase_out(p, l, lds); xcd_barrier(xb);
;     phase_ple(p, l, lds); if (l + 1 < NL) xcd_barrier(xb);
.LBB0_50:
	s_waitcnt lgkmcnt(0)
	s_load_dwordx16 s[68:83], s[0:1], 0x80
	v_readlane_b32 s26, v251, 0
	s_sub_i32 s2, s26, 32
	s_cmp_lt_i32 s26, 32
	s_cselect_b64 s[0:1], -1, 0
	s_waitcnt lgkmcnt(0)
	v_writelane_b32 v252, s68, 3
	s_and_b64 s[0:1], s[0:1], exec
	s_cselect_b32 s20, s26, s2
	v_writelane_b32 v252, s69, 4
	v_writelane_b32 v252, s70, 5
	v_writelane_b32 v252, s71, 6
	v_writelane_b32 v252, s72, 7
	v_writelane_b32 v252, s73, 8
	v_writelane_b32 v252, s74, 9
	v_writelane_b32 v252, s75, 10
	v_writelane_b32 v252, s76, 11
	v_writelane_b32 v252, s77, 12
	v_writelane_b32 v252, s78, 13
	v_writelane_b32 v252, s79, 14
	v_writelane_b32 v252, s80, 15
	s_lshl_b32 s0, s20, 1
	v_writelane_b32 v252, s81, 16
	s_lshl_b32 s28, s26, 7
	s_add_i32 s2, s0, 0x1000
	v_writelane_b32 v252, s82, 17
	s_cmp_lt_i32 s26, 32
	v_writelane_b32 v252, s83, 18
	s_cselect_b64 s[0:1], -1, 0
	v_writelane_b32 v252, s0, 19
	v_readlane_b32 s68, v251, 49
	v_readlane_b32 s70, v251, 51
	v_writelane_b32 v252, s1, 20
	s_and_b64 s[0:1], s[0:1], exec
	s_cselect_b32 s24, 0x80, 2
	s_cselect_b32 s96, s28, s2
	s_lshr_b32 s21, s26, 3
	s_lshr_b32 s27, s90, 3
	s_cmp_lt_u32 s21, s27
	s_cselect_b64 s[2:3], -1, 0
	s_and_b32 s29, s26, 7
	s_mul_i32 s0, s29, 0x1944
	s_lshr_b32 s1, s0, 3
	s_addk_i32 s0, 0x1944
	s_lshr_b32 s31, s0, 3
	s_add_i32 s34, s1, s21
	s_cmp_lt_u32 s34, s31
	s_cselect_b64 s[0:1], -1, 0
	v_writelane_b32 v252, s29, 21
	s_and_b64 s[0:1], s[2:3], s[0:1]
	v_writelane_b32 v252, s0, 22
	v_readlane_b32 s71, v251, 52
	v_readlane_b32 s69, v251, 50
	v_writelane_b32 v252, s1, 23
	s_add_u32 s0, s70, 0x1481a000
	v_readlane_b32 s83, v252, 0
	v_writelane_b32 v252, s0, 24
	s_addc_u32 s0, s71, 0
	v_writelane_b32 v252, s0, 25
	s_add_u32 s0, s70, 0xc200000
	v_writelane_b32 v252, s0, 26
	s_addc_u32 s0, s71, 0
	v_writelane_b32 v252, s0, 27
	s_add_u32 s0, s70, 0x1441a000
	v_writelane_b32 v252, s0, 28
	s_addc_u32 s0, s71, 0
	v_writelane_b32 v252, s0, 29
	s_add_u32 s0, s70, 0x4200000
	v_writelane_b32 v252, s0, 30
	s_addc_u32 s0, s71, 0
	v_writelane_b32 v252, s0, 31
	s_add_u32 s0, s70, 0x1501a000
	s_addc_u32 s1, s71, 0
	v_writelane_b32 v252, s0, 32
	v_readlane_b32 s72, v251, 53
	v_readlane_b32 s73, v251, 54
	v_writelane_b32 v252, s1, 33
	s_add_u32 s0, s70, 0x14400000
	v_writelane_b32 v252, s0, 34
	s_addc_u32 s0, s71, 0
	v_writelane_b32 v252, s0, 35
	s_lshl_b32 s0, s26, 8
	s_lshl_b32 s35, s90, 8
	s_cmpk_lt_i32 s26, 0x140
	v_writelane_b32 v252, s0, 36
	s_cselect_b64 s[0:1], -1, 0
	s_add_u32 s92, s66, 0x200
	s_addc_u32 s93, s67, 0
	s_add_u32 s22, s66, 0x1000
	s_addc_u32 s23, s67, 0
	v_writelane_b32 v252, s22, 37
	v_readlane_b32 s74, v251, 55
	v_readlane_b32 s75, v251, 56
	v_writelane_b32 v252, s23, 38
	s_add_u32 s22, s66, 0x1100
	s_addc_u32 s23, s67, 0
	v_writelane_b32 v252, s22, 39
	v_readlane_b32 s76, v251, 57
	v_readlane_b32 s77, v251, 58
	v_writelane_b32 v252, s23, 40
	s_add_u32 s22, s66, 0x1200
	s_addc_u32 s23, s67, 0
	v_writelane_b32 v252, s22, 41
	v_readlane_b32 s78, v251, 59
	v_readlane_b32 s79, v251, 60
	v_writelane_b32 v252, s23, 42
	s_add_u32 s22, s66, 0x1300
	s_addc_u32 s23, s67, 0
	v_writelane_b32 v252, s22, 43
	s_cmp_eq_u32 s36, 15
	v_readlane_b32 s80, v251, 61
	v_writelane_b32 v252, s23, 44
	s_cselect_b64 s[22:23], -1, 0
	v_writelane_b32 v252, s22, 45
	s_cmp_eq_u32 s36, 14
	v_readlane_b32 s81, v251, 62
	v_writelane_b32 v252, s23, 46
	s_cselect_b64 s[22:23], -1, 0
	v_writelane_b32 v252, s22, 47
	s_cmp_eq_u32 s36, 13
	v_readlane_b32 s82, v251, 63
	v_writelane_b32 v252, s23, 48
	s_cselect_b64 s[22:23], -1, 0
	v_writelane_b32 v252, s22, 49
	s_cmp_eq_u32 s36, 12
	v_readlane_b32 s68, v251, 17
	v_writelane_b32 v252, s23, 50
	s_cselect_b64 s[22:23], -1, 0
	v_writelane_b32 v252, s22, 51
	s_cmp_eq_u32 s36, 11
	v_readlane_b32 s74, v251, 23
	v_writelane_b32 v252, s23, 52
	s_cselect_b64 s[22:23], -1, 0
	v_writelane_b32 v252, s22, 53
	s_cmp_eq_u32 s36, 10
	v_readlane_b32 s75, v251, 24
	v_writelane_b32 v252, s23, 54
	s_cselect_b64 s[22:23], -1, 0
	v_writelane_b32 v252, s22, 55
	s_cmp_eq_u32 s36, 9
	v_readlane_b32 s82, v251, 31
	v_writelane_b32 v252, s23, 56
	s_cselect_b64 s[22:23], -1, 0
	v_writelane_b32 v252, s22, 57
	s_cmp_eq_u32 s36, 8
	v_readlane_b32 s83, v251, 32
	v_writelane_b32 v252, s23, 58
	s_cselect_b64 s[22:23], -1, 0
	v_writelane_b32 v252, s22, 59
	s_cmp_eq_u32 s36, 7
	v_readlane_b32 s78, v251, 27
	v_writelane_b32 v252, s23, 60
	s_cselect_b64 s[22:23], -1, 0
	v_writelane_b32 v252, s22, 61
	s_cmp_eq_u32 s36, 6
	v_readlane_b32 s79, v251, 28
	v_writelane_b32 v252, s23, 62
	s_cselect_b64 s[22:23], -1, 0
	v_writelane_b32 v252, s22, 63
	s_cmp_eq_u32 s36, 5
	s_mov_b32 s97, 0
	v_writelane_b32 v253, s23, 0
	s_cselect_b64 s[22:23], -1, 0
	v_writelane_b32 v253, s22, 1
	s_cmp_eq_u32 s36, 4
	v_readlane_b32 s69, v251, 18
	v_writelane_b32 v253, s23, 2
	s_cselect_b64 s[22:23], -1, 0
	v_writelane_b32 v253, s22, 3
	s_cmp_eq_u32 s36, 3
	v_readlane_b32 s70, v251, 19
	v_writelane_b32 v253, s23, 4
	s_cselect_b64 s[22:23], -1, 0
	v_writelane_b32 v253, s22, 5
	s_cmp_eq_u32 s36, 2
	v_readlane_b32 s71, v251, 20
	v_writelane_b32 v253, s23, 6
	s_cselect_b64 s[22:23], -1, 0
	v_writelane_b32 v253, s22, 7
	s_cmp_eq_u32 s36, 1
	v_readlane_b32 s72, v251, 21
	v_writelane_b32 v253, s23, 8
	s_cselect_b64 s[22:23], -1, 0
	v_writelane_b32 v253, s22, 9
	s_cmp_eq_u32 s36, 0
	v_readlane_b32 s73, v251, 22
	v_writelane_b32 v253, s23, 10
	s_cselect_b64 s[22:23], -1, 0
	v_writelane_b32 v253, s22, 11
	v_readlane_b32 s76, v251, 25
	v_readlane_b32 s77, v251, 26
	v_writelane_b32 v253, s23, 12
	s_lshl_b32 s22, s36, 8
	s_add_u32 s22, s66, s22
	s_addc_u32 s23, s67, 0
	s_add_u32 s36, s22, 0x1400
	s_addc_u32 s37, s23, 0
	v_writelane_b32 v253, s36, 13
; __global__ void __launch_bounds__(256, 2) k_mega(Params p) {
;     ...
; #pragma unroll 1
;   for (int l = 0; l < NL; ++l) {
;     phase_gemm_in(p, l, lds); xcd_barrier(xb);
;     phase_chunk(p, l, lds); xcd_barrier(xb);
;     phase_mix(p, l, lds); xcd_barrier(xb);
;     phase_o(p, l, blockIdx.x, NCH_P / 2, gridDim.x); xcd_barrier(xb);
;     phase_merge(p, l, lds); xcd_barrier(xb);
;     phase_out(p, l, lds); xcd_barrier(xb);
;     phase_ple(p, l, lds); if (l + 1 < NL) xcd_barrier(xb);
	s_add_u32 s22, s22, 0x2400
	s_addc_u32 s23, s23, 0
	v_writelane_b32 v253, s37, 14
	v_writelane_b32 v253, s22, 15
	v_readlane_b32 s36, v252, 3
	v_readlane_b32 s38, v252, 5
	v_writelane_b32 v253, s23, 16
	s_add_u32 s22, s66, 0x3400
	s_addc_u32 s23, s67, 0
	v_writelane_b32 v253, s22, 17
	v_readlane_b32 s39, v252, 6
	v_readlane_b32 s37, v252, 4
	v_writelane_b32 v253, s23, 18
	s_add_u32 s22, s66, 0x3500
	s_addc_u32 s23, s67, 0
	v_writelane_b32 v253, s22, 19
	s_cmpk_lt_i32 s26, 0x1000
	v_readlane_b32 s42, v252, 9
	v_writelane_b32 v253, s23, 20
	s_cselect_b64 s[22:23], -1, 0
	v_writelane_b32 v253, s22, 21
	s_cmpk_lt_u32 s26, 0x60
	v_readlane_b32 s43, v252, 10
	v_writelane_b32 v253, s23, 22
	s_cselect_b64 s[22:23], -1, 0
	v_writelane_b32 v253, s22, 23
	s_cmp_gt_u32 s26, 31
	v_readlane_b32 s80, v251, 29
	v_writelane_b32 v253, s23, 24
	s_cselect_b64 s[22:23], -1, 0
	v_writelane_b32 v253, s22, 25
	s_lshl_b32 s25, s26, 1
	v_readlane_b32 s81, v251, 30
	v_writelane_b32 v253, s23, 26
	s_sub_i32 s22, s25, 64
	s_lshr_b32 s23, s22, 4
	v_writelane_b32 v253, s23, 27
	s_lshl_b32 s23, s23, 6
	s_addk_i32 s23, 0x4000
	s_lshl_b32 s22, s22, 5
	v_writelane_b32 v253, s23, 28
	s_and_b32 s22, s22, 0x1c0
	s_add_i32 s23, s25, 0xfc0
	v_writelane_b32 v253, s23, 29
	s_lshl_b32 s23, s22, 7
	v_writelane_b32 v253, s23, 30
	v_writelane_b32 v253, s22, 31
	s_lshl_b32 s22, s22, 2
	s_add_u32 s23, s74, s22
	v_writelane_b32 v253, s23, 32
	s_addc_u32 s23, s75, 0
	v_writelane_b32 v253, s23, 33
	s_add_u32 s23, s82, s22
	v_writelane_b32 v253, s23, 34
	s_addc_u32 s23, s83, 0
	v_writelane_b32 v253, s23, 35
	s_add_u32 s23, s38, s22
	v_writelane_b32 v253, s23, 36
	s_addc_u32 s23, s39, 0
	v_writelane_b32 v253, s23, 37
	s_add_u32 s23, s78, s22
	v_writelane_b32 v253, s23, 38
	s_addc_u32 s23, s79, 0
	v_writelane_b32 v253, s23, 39
	s_add_u32 s23, s36, s22
	v_writelane_b32 v253, s23, 40
	s_addc_u32 s23, s37, 0
	v_writelane_b32 v253, s23, 41
	s_add_u32 s22, s42, s22
	v_writelane_b32 v253, s22, 42
	s_addc_u32 s22, s43, 0
	s_cmp_gt_i32 s26, 31
	v_writelane_b32 v253, s22, 43
	s_cselect_b64 s[22:23], -1, 0
	v_writelane_b32 v253, s22, 44
	v_readlane_b32 s68, v251, 49
	v_readlane_b32 s72, v251, 53
	v_writelane_b32 v253, s23, 45
	s_ashr_i32 s22, s20, 3
	s_lshl_b32 s20, s20, 6
	v_writelane_b32 v253, s22, 46
	s_and_b32 s36, s20, 0x1c0
	s_lshl_b64 s[22:23], s[96:97], 13
	s_add_u32 s38, s88, s22
	s_addc_u32 s39, s89, s23
	v_writelane_b32 v253, s38, 47
	s_add_i32 s20, s24, -2
	s_add_i32 s24, s24, -1
	v_writelane_b32 v253, s39, 48
	s_add_u32 s38, s56, s22
	v_writelane_b32 v253, s20, 49
	s_addc_u32 s39, s57, s23
	v_writelane_b32 v253, s38, 50
	s_add_u32 s22, s58, s22
	s_addc_u32 s23, s59, s23
	v_writelane_b32 v253, s39, 51
	v_writelane_b32 v253, s22, 52
	v_readlane_b32 s73, v251, 54
	s_mov_b32 s37, s97
	v_writelane_b32 v253, s23, 53
	s_or_b32 s22, s96, 1
	s_mov_b32 s23, s97
	s_lshl_b64 s[22:23], s[22:23], 13
	s_add_u32 s38, s56, s22
	s_addc_u32 s39, s57, s23
	s_add_u32 s22, s58, s22
	v_writelane_b32 v253, s38, 54
	s_addc_u32 s23, s59, s23
	s_min_u32 s20, s24, 2
	v_writelane_b32 v253, s39, 55
	s_or_b32 s20, s20, s28
	v_writelane_b32 v253, s22, 56
	s_lshl_b32 s20, s20, 13
	v_readlane_b32 s78, v251, 59
	v_writelane_b32 v253, s23, 57
	s_add_u32 s22, s58, s20
	s_addc_u32 s23, s59, 0
	v_writelane_b32 v253, s22, 58
	v_readlane_b32 s79, v251, 60
	v_readlane_b32 s82, v251, 63
	v_writelane_b32 v253, s23, 59
	s_add_u32 s22, s56, s20
	s_addc_u32 s23, s57, 0
	v_writelane_b32 v253, s22, 60
	v_readlane_b32 s83, v252, 0
	v_readlane_b32 s49, v252, 16
	v_writelane_b32 v253, s23, 61
	s_add_i32 s22, s96, s24
	s_mov_b32 s23, s97
	s_lshl_b64 s[22:23], s[22:23], 13
	s_add_u32 s22, s88, s22
	v_writelane_b32 v253, s24, 62
	s_addc_u32 s23, s89, s23
	v_writelane_b32 v253, s22, 63
	s_mov_b32 s49, s27
	v_readlane_b32 s50, v252, 17
	v_writelane_b32 v254, s23, 0
	s_add_u32 s22, s88, 0x2100000
	s_addc_u32 s23, s89, 0
	v_writelane_b32 v254, s22, 1
	s_sub_i32 s20, 64, s25
	s_cmpk_lg_i32 s90, 0x200
	v_writelane_b32 v254, s23, 2
	v_writelane_b32 v254, s25, 3
	v_writelane_b32 v254, s20, 4
	s_cselect_b64 s[22:23], -1, 0
	s_and_b32 s20, s26, 0xffffffe0
	s_cmpk_lg_i32 s20, 0x100
	s_cselect_b64 s[24:25], -1, 0
	s_or_b64 s[22:23], s[24:25], s[22:23]
	s_lshl_b32 s20, s29, 2
	v_writelane_b32 v254, s22, 5
	s_add_u32 s20, s66, s20
	v_readlane_b32 s51, v252, 18
	v_writelane_b32 v254, s23, 6
	s_addc_u32 s22, s67, 0
	s_add_u32 s20, s20, 0x3600
	v_writelane_b32 v254, s20, 7
	s_addc_u32 s20, s22, 0
	s_cmpk_lt_i32 s26, 0x800
	v_writelane_b32 v254, s20, 8
	s_cselect_b64 s[22:23], -1, 0
	s_lshl_b32 s20, s29, 7
	s_add_i32 s38, s20, s21
	s_lshl_b32 s20, s29, 10
	s_addk_i32 s20, 0x400
	v_writelane_b32 v254, s22, 9
	s_lshr_b32 s20, s20, 3
	s_cmp_lt_u32 s38, s20
; #define LAS __attribute__((address_space(3)))
; __global__ void __launch_bounds__(256, 2) k_mega(Params p) {
;     ...
;   if (threadIdx.x == 0) xb_words = make_uint4(0u, 0u, 0u, 0u);
;   __syncthreads();
;   const XcdBarrier xb = xcd_barrier_post(p.bar, (volatile LAS unsigned*)&xb_words);
;   phase_norm0(p, lds);
;   grid.sync();
; #pragma unroll 1
	v_writelane_b32 v254, s23, 10
	v_writelane_b32 v254, s20, 11
	s_cselect_b64 s[20:21], -1, 0
	s_and_b64 s[2:3], s[2:3], s[20:21]
	v_writelane_b32 v254, s2, 12
	s_cmpk_lt_i32 s26, 0x200
	s_mov_b32 s29, s97
	v_writelane_b32 v254, s3, 13
	s_mul_i32 s2, s91, s90
	s_mul_i32 s2, s2, s33
	v_writelane_b32 v254, s2, 14
	s_cselect_b64 s[2:3], -1, 0
	v_writelane_b32 v254, s2, 15
	s_cmpk_lt_i32 s26, 0x1030
	v_readlane_b32 s45, v252, 12
	v_writelane_b32 v254, s3, 16
	s_cselect_b64 s[2:3], -1, 0
	v_writelane_b32 v254, s2, 17
	v_readlane_b32 s50, v252, 1
	v_mov_b32_e32 v1, 0
	v_writelane_b32 v254, s3, 18
	s_add_u32 s2, s8, 0x80
	s_addc_u32 s3, s9, 0
	v_writelane_b32 v254, s2, 19
	v_mov_b32_e32 v249, 0x358637bd
	v_mov_b32_e32 v210, 0x12000
	v_writelane_b32 v254, s3, 20
	s_add_u32 s2, s72, 0x80
	s_addc_u32 s3, s73, 0
	v_writelane_b32 v254, s2, 21
	v_mov_b32_e32 v211, 0x12004
	v_mbcnt_hi_u32_b32 v218, -1, v213
	v_writelane_b32 v254, s3, 22
	v_writelane_b32 v254, s28, 23
	s_add_i32 s2, s96, 2
	v_mov_b32_e32 v219, 0x260
	v_writelane_b32 v254, s29, 24
	v_writelane_b32 v254, s2, 25
	s_lshl_b64 s[2:3], s[28:29], 13
	s_add_u32 s2, s88, s2
	s_addc_u32 s3, s89, s3
	s_add_u32 s2, s2, 0x2040
	s_addc_u32 s3, s3, 0
	v_writelane_b32 v254, s2, 26
	v_mov_b32_e32 v221, 0x12010
	v_mov_b32_e32 v250, 0x4000
	v_writelane_b32 v254, s3, 27
	v_writelane_b32 v254, s36, 28
	s_or_b32 s2, s28, 3
	v_mov_b32_e32 v220, 0x6000
	v_writelane_b32 v254, s37, 29
	v_writelane_b32 v254, s2, 30
	s_add_u32 s2, s18, 0x80
	v_writelane_b32 v254, s2, 31
	s_addc_u32 s2, s19, 0
	v_writelane_b32 v254, s2, 32
	s_lshl_b32 s2, s90, 1
	v_writelane_b32 v254, s2, 33
	s_lshl_b32 s3, s26, 5
	s_lshl_b32 s2, s90, 5
	s_add_u32 s20, s78, 0x80
	v_writelane_b32 v254, s2, 34
	s_addc_u32 s21, s79, 0
	v_writelane_b32 v254, s20, 35
	v_mov_b32_e32 v248, 0x400
	v_mov_b32_e32 v230, 0x41b17218
	v_writelane_b32 v254, s21, 36
	s_add_u32 s20, s52, 0x80
	s_addc_u32 s21, s53, 0
	v_writelane_b32 v254, s20, 37
	v_mov_b32_e32 v231, 0x100000
	v_mov_b32_e32 v160, 0x3e38aa3b
	v_writelane_b32 v254, s21, 38
	s_add_u32 s20, s82, 0x80
	s_addc_u32 s21, s83, 0
	v_writelane_b32 v254, s20, 39
	s_lshl_b32 s2, s26, 12
	s_add_i32 s2, s2, 0xff7d0000
	v_writelane_b32 v254, s21, 40
	v_writelane_b32 v254, s2, 41
	s_lshl_b32 s2, s26, 2
	s_addk_i32 s2, 0xcf40
	v_writelane_b32 v254, s2, 42
	s_lshl_b32 s2, s26, 3
	s_addk_i32 s2, 0x9e80
	v_writelane_b32 v254, s2, 43
	s_xor_b64 s[0:1], s[0:1], -1
	v_writelane_b32 v254, s0, 44
	s_movk_i32 s91, 0x4000
	s_mov_b32 s33, 0x8000
	v_writelane_b32 v254, s1, 45
	v_writelane_b32 v254, s3, 46
	s_add_i32 s0, s3, 0xfffefa00
	v_writelane_b32 v254, s0, 47
	s_lshl_b32 s0, s26, 6
	v_writelane_b32 v254, s0, 48
	s_lshl_b32 s0, s90, 6
	v_writelane_b32 v254, s0, 49
	s_lshl_b32 s0, s90, 12
	v_writelane_b32 v254, s0, 50
	s_lshl_b32 s0, s90, 2
	s_mov_b64 s[20:21], s[84:85]
	v_writelane_b32 v254, s0, 51
	s_mov_b64 s[22:23], s[86:87]
	s_mov_b64 s[24:25], s[88:89]
	s_mov_b32 s26, s90
	v_writelane_b32 v254, s20, 52
	s_lshl_b32 s0, s90, 3
	s_mov_b32 s87, s38
	v_writelane_b32 v254, s21, 53
	v_writelane_b32 v254, s22, 54
	v_writelane_b32 v254, s23, 55
	v_writelane_b32 v254, s24, 56
	v_writelane_b32 v254, s25, 57
	v_writelane_b32 v254, s26, 58
	v_writelane_b32 v254, s27, 59
	v_writelane_b32 v254, s0, 60
	v_writelane_b32 v254, s92, 61
	s_mov_b32 s86, s35
	s_mov_b32 s85, s34
	s_mov_b32 s84, s31
	s_mov_b32 s34, 0x800000
	s_movk_i32 s94, 0x3100
	s_movk_i32 s45, 0x41ff
	s_movk_i32 s90, 0x90
	s_movk_i32 s95, 0x50
	s_mov_b32 s35, 0x3e38aa3b
	s_mov_b64 s[28:29], 0x80
	s_mov_b64 s[88:89], 0x380
	s_mov_b32 s20, s97
	v_readlane_b32 s51, v252, 2
	v_writelane_b32 v254, s93, 62
	v_readlane_b32 s40, v252, 7
	v_readlane_b32 s41, v252, 8
	v_readlane_b32 s44, v252, 11
	v_readlane_b32 s46, v252, 13
	v_readlane_b32 s47, v252, 14
	v_readlane_b32 s48, v252, 15
	v_readlane_b32 s69, v251, 50
	v_readlane_b32 s70, v251, 51
	v_readlane_b32 s71, v251, 52
	v_readlane_b32 s74, v251, 55
	v_readlane_b32 s75, v251, 56
	v_readlane_b32 s76, v251, 57
	v_readlane_b32 s77, v251, 58
	v_readlane_b32 s80, v251, 61
	v_readlane_b32 s81, v251, 62
	s_waitcnt vmcnt(0) lgkmcnt(0)
	s_barrier
	s_and_saveexec_b64 s[0:1], s[50:51]
	s_cbranch_execz .Lgsync_done
	buffer_wbl2 sc1
	s_waitcnt vmcnt(0)
	v_mov_b32_e32 v2, 1
	global_atomic_add v1, v2, s[66:67]
	v_readlane_b32 s21, v254, 14
	s_waitcnt vmcnt(0)
	s_mov_b32 s23, 0
.Lgsync_spin:
	global_load_dword v2, v1, s[66:67] sc1
	s_waitcnt vmcnt(0)
	v_readfirstlane_b32 s22, v2
	s_nop 3
	s_cmp_lt_u32 s22, s21
	s_cbranch_scc0 .Lgsync_arrived
	s_sleep 1
	s_add_i32 s23, s23, 1
	s_cmp_lt_u32 s23, 0x400000
	s_cbranch_scc1 .Lgsync_spin
.Lgsync_arrived:
	buffer_inv sc1
	s_waitcnt vmcnt(0)
.Lgsync_done:
	s_or_b64 exec, exec, s[0:1]
	s_barrier
	s_branch .LBB0_64

; DI void chunk_item(const Params& p, int l, int item, char* lds) {
;     ...
;   if (tid < 64) {
;     float run = 0.f;
; #pragma unroll 8
;     for (int t = 0; t < 32; ++t) { run += s_w[t * 64 + tid]; s_w[t * 64 + tid] = run; }
;   }
.LBB0_286:
	s_waitcnt lgkmcnt(0)
	ds_read2st64_b32 v[32:33], v26 offset0:0 offset1:1
	ds_read2st64_b32 v[34:35], v26 offset0:2 offset1:3
	ds_read2st64_b32 v[36:37], v26 offset0:4 offset1:5
	ds_read2st64_b32 v[38:39], v26 offset0:6 offset1:7
	ds_read2st64_b32 v[40:41], v26 offset0:8 offset1:9
	ds_read2st64_b32 v[70:71], v26 offset0:10 offset1:11
	ds_read2st64_b32 v[72:73], v26 offset0:12 offset1:13
	ds_read2st64_b32 v[74:75], v26 offset0:14 offset1:15
	ds_read2st64_b32 v[76:77], v26 offset0:16 offset1:17
	ds_read2st64_b32 v[78:79], v26 offset0:18 offset1:19
	ds_read2st64_b32 v[114:115], v26 offset0:20 offset1:21
	ds_read2st64_b32 v[116:117], v26 offset0:22 offset1:23
	ds_read2st64_b32 v[118:119], v26 offset0:24 offset1:25
	ds_read2st64_b32 v[120:121], v26 offset0:26 offset1:27
	ds_read2st64_b32 v[122:123], v26 offset0:28 offset1:29
	s_waitcnt lgkmcnt(14)
	v_add_f32_e32 v33, v32, v33
	ds_read2st64_b32 v[124:125], v26 offset0:30 offset1:31
	s_waitcnt lgkmcnt(14)
	v_add_f32_e32 v34, v33, v34
	v_add_f32_e32 v35, v34, v35
	s_waitcnt lgkmcnt(13)
	v_add_f32_e32 v36, v35, v36
	v_add_f32_e32 v37, v36, v37
	s_waitcnt lgkmcnt(12)
	v_add_f32_e32 v38, v37, v38
	v_add_f32_e32 v39, v38, v39
	s_waitcnt lgkmcnt(11)
	v_add_f32_e32 v40, v39, v40
	v_add_f32_e32 v41, v40, v41
	s_waitcnt lgkmcnt(10)
	v_add_f32_e32 v70, v41, v70
	v_add_f32_e32 v71, v70, v71
	s_waitcnt lgkmcnt(9)
	v_add_f32_e32 v72, v71, v72
	v_add_f32_e32 v73, v72, v73
	s_waitcnt lgkmcnt(8)
	v_add_f32_e32 v74, v73, v74
	v_add_f32_e32 v75, v74, v75
	s_waitcnt lgkmcnt(7)
	v_add_f32_e32 v76, v75, v76
	v_add_f32_e32 v77, v76, v77
	s_waitcnt lgkmcnt(6)
	v_add_f32_e32 v78, v77, v78
	v_add_f32_e32 v79, v78, v79
	s_waitcnt lgkmcnt(5)
	v_add_f32_e32 v114, v79, v114
	v_add_f32_e32 v115, v114, v115
	s_waitcnt lgkmcnt(4)
	v_add_f32_e32 v116, v115, v116
	v_add_f32_e32 v117, v116, v117
	s_waitcnt lgkmcnt(3)
	v_add_f32_e32 v118, v117, v118
	v_add_f32_e32 v119, v118, v119
	s_waitcnt lgkmcnt(2)
	v_add_f32_e32 v120, v119, v120
	v_add_f32_e32 v121, v120, v121
	s_waitcnt lgkmcnt(1)
	v_add_f32_e32 v122, v121, v122
	v_add_f32_e32 v123, v122, v123
	s_waitcnt lgkmcnt(0)
	v_add_f32_e32 v124, v123, v124
	v_add_f32_e32 v125, v124, v125
	ds_write2st64_b32 v26, v32, v33 offset0:0 offset1:1
	ds_write2st64_b32 v26, v34, v35 offset0:2 offset1:3
	ds_write2st64_b32 v26, v36, v37 offset0:4 offset1:5
	ds_write2st64_b32 v26, v38, v39 offset0:6 offset1:7
	ds_write2st64_b32 v26, v40, v41 offset0:8 offset1:9
	ds_write2st64_b32 v26, v70, v71 offset0:10 offset1:11
	ds_write2st64_b32 v26, v72, v73 offset0:12 offset1:13
	ds_write2st64_b32 v26, v74, v75 offset0:14 offset1:15
	s_waitcnt lgkmcnt(0)
	ds_write2st64_b32 v26, v76, v77 offset0:16 offset1:17
	ds_write2st64_b32 v26, v78, v79 offset0:18 offset1:19
	ds_write2st64_b32 v26, v114, v115 offset0:20 offset1:21
	ds_write2st64_b32 v26, v116, v117 offset0:22 offset1:23
	ds_write2st64_b32 v26, v118, v119 offset0:24 offset1:25
	ds_write2st64_b32 v26, v120, v121 offset0:26 offset1:27
	ds_write2st64_b32 v26, v122, v123 offset0:28 offset1:29
	ds_write2st64_b32 v26, v124, v125 offset0:30 offset1:31
